# first seam: cg grid.sync replaced by the xcd barrier
# speedup vs baseline: 1.0124x; 1.0124x over previous
.LBB0_1875:
	s_waitcnt vmcnt(0)
	s_waitcnt lgkmcnt(0)
	s_barrier
	s_mov_b64 s[0:1], exec
	v_readlane_b32 s20, v235, 3
	v_readlane_b32 s21, v235, 4
	s_and_b64 s[20:21], s[0:1], s[20:21]
	s_mov_b64 exec, s[20:21]
	s_cbranch_execz .LBB0_1934
	s_waitcnt vmcnt(0) expcnt(0) lgkmcnt(0)
	ds_read_b32 v2, v166
	ds_read_b32 v0, v167
	s_waitcnt lgkmcnt(1)
	v_cmp_ne_u32_e32 vcc, 0, v2
	s_cbranch_vccnz .LBB0_1898
	s_mov_b32 s24, 1
	s_branch .LBB0_1880
